# K loops: counted lgkmcnt waits at the first MFMA consuming each LDS fragment instead of lgkmcnt(0) before the group
# speedup vs baseline: 1.0161x; 1.0014x over previous
.LBB0_236:
	ds_read_b128 v[144:147], v160
	ds_read_b128 v[148:151], v161
	ds_read_b128 v[178:181], v163
	ds_read_b128 v[182:185], v164
	s_add_i32 s14, s2, 2
	s_add_u32 s8, s6, 0x80
	s_addc_u32 s3, s7, 0
	s_cmp_eq_u32 s56, s2
	s_cselect_b32 s2, s62, s8
	s_cselect_b32 s3, s63, s3
	s_cselect_b32 s9, s1, s11
	s_cselect_b32 s8, s0, s10
	s_mov_b32 m0, s61
	ds_read_b128 v[186:189], v158
	ds_read_b128 v[190:193], v158 offset:1024
	ds_read_b128 v[194:197], v158 offset:2048
	ds_read_b128 v[198:201], v158 offset:3072
	ds_read_b128 v[202:205], v158 offset:4096
	ds_read_b128 v[206:209], v158 offset:5120
	ds_read_b128 v[210:213], v158 offset:6144
	ds_read_b128 v[214:217], v158 offset:7168
	global_load_lds_dwordx4 v136, s[6:7]
	s_mov_b32 m0, s64
	s_nop 0
	global_load_lds_dwordx4 v138, s[6:7]
	s_waitcnt lgkmcnt(8)
	s_barrier
	s_waitcnt lgkmcnt(7)
	v_mfma_f32_16x16x32_bf16 v[126:129], v[144:147], v[186:189], v[126:129]
	v_mfma_f32_16x16x32_bf16 v[122:125], v[178:181], v[186:189], v[122:125]
	s_waitcnt lgkmcnt(5)
	v_mfma_f32_16x16x32_bf16 v[110:113], v[144:147], v[194:197], v[110:113]
	v_mfma_f32_16x16x32_bf16 v[106:109], v[178:181], v[194:197], v[106:109]
	s_waitcnt lgkmcnt(3)
	v_mfma_f32_16x16x32_bf16 v[94:97], v[144:147], v[202:205], v[94:97]
	v_mfma_f32_16x16x32_bf16 v[90:93], v[178:181], v[202:205], v[90:93]
	s_waitcnt lgkmcnt(1)
	v_mfma_f32_16x16x32_bf16 v[78:81], v[144:147], v[210:213], v[78:81]
	v_mfma_f32_16x16x32_bf16 v[74:77], v[178:181], v[210:213], v[74:77]
	v_mfma_f32_16x16x32_bf16 v[126:129], v[148:151], v[190:193], v[126:129]
	v_mfma_f32_16x16x32_bf16 v[122:125], v[182:185], v[190:193], v[122:125]
	v_mfma_f32_16x16x32_bf16 v[110:113], v[148:151], v[198:201], v[110:113]
	v_mfma_f32_16x16x32_bf16 v[106:109], v[182:185], v[198:201], v[106:109]
	v_mfma_f32_16x16x32_bf16 v[94:97], v[148:151], v[206:209], v[94:97]
	v_mfma_f32_16x16x32_bf16 v[90:93], v[182:185], v[206:209], v[90:93]
	s_waitcnt lgkmcnt(0)
	v_mfma_f32_16x16x32_bf16 v[78:81], v[148:151], v[214:217], v[78:81]
	v_mfma_f32_16x16x32_bf16 v[74:77], v[182:185], v[214:217], v[74:77]
	s_barrier
	s_mov_b32 m0, s30
	ds_read_b128 v[218:221], v165
	ds_read_b128 v[222:225], v166
	ds_read_b128 v[226:229], v167
	ds_read_b128 v[230:233], v168
	global_load_lds_dwordx4 v130, s[8:9]
	s_mov_b32 m0, s31
	s_nop 0
	global_load_lds_dwordx4 v132, s[8:9]
	s_barrier
	s_waitcnt lgkmcnt(3)
	v_mfma_f32_16x16x32_bf16 v[118:121], v[218:221], v[186:189], v[118:121]
	s_waitcnt lgkmcnt(1)
	v_mfma_f32_16x16x32_bf16 v[114:117], v[226:229], v[186:189], v[114:117]
	v_mfma_f32_16x16x32_bf16 v[102:105], v[218:221], v[194:197], v[102:105]
	v_mfma_f32_16x16x32_bf16 v[98:101], v[226:229], v[194:197], v[98:101]
	v_mfma_f32_16x16x32_bf16 v[86:89], v[218:221], v[202:205], v[86:89]
	v_mfma_f32_16x16x32_bf16 v[82:85], v[226:229], v[202:205], v[82:85]
	v_mfma_f32_16x16x32_bf16 v[70:73], v[218:221], v[210:213], v[70:73]
	v_mfma_f32_16x16x32_bf16 v[66:69], v[226:229], v[210:213], v[66:69]
	v_mfma_f32_16x16x32_bf16 v[118:121], v[222:225], v[190:193], v[118:121]
	s_waitcnt lgkmcnt(0)
	v_mfma_f32_16x16x32_bf16 v[114:117], v[230:233], v[190:193], v[114:117]
	v_mfma_f32_16x16x32_bf16 v[102:105], v[222:225], v[198:201], v[102:105]
	v_mfma_f32_16x16x32_bf16 v[98:101], v[230:233], v[198:201], v[98:101]
	v_mfma_f32_16x16x32_bf16 v[86:89], v[222:225], v[206:209], v[86:89]
	v_mfma_f32_16x16x32_bf16 v[82:85], v[230:233], v[206:209], v[82:85]
	v_mfma_f32_16x16x32_bf16 v[70:73], v[222:225], v[214:217], v[70:73]
	v_mfma_f32_16x16x32_bf16 v[66:69], v[230:233], v[214:217], v[66:69]
	s_mov_b32 m0, s29
	s_barrier
	ds_read_b128 v[186:189], v158 offset:16384
	ds_read_b128 v[190:193], v158 offset:17408
	ds_read_b128 v[194:197], v158 offset:18432
	ds_read_b128 v[198:201], v158 offset:19456
	ds_read_b128 v[202:205], v158 offset:20480
	ds_read_b128 v[206:209], v158 offset:21504
	ds_read_b128 v[210:213], v158 offset:22528
	ds_read_b128 v[214:217], v158 offset:23552
	global_load_lds_dwordx4 v130, s[2:3]
	s_mov_b32 m0, s33
	s_nop 0
	global_load_lds_dwordx4 v132, s[2:3]
	s_barrier
	s_waitcnt lgkmcnt(7)
	v_mfma_f32_16x16x32_bf16 v[62:65], v[144:147], v[186:189], v[62:65]
	v_mfma_f32_16x16x32_bf16 v[58:61], v[178:181], v[186:189], v[58:61]
	s_waitcnt lgkmcnt(5)
	v_mfma_f32_16x16x32_bf16 v[46:49], v[144:147], v[194:197], v[46:49]
	v_mfma_f32_16x16x32_bf16 v[42:45], v[178:181], v[194:197], v[42:45]
	s_waitcnt lgkmcnt(3)
	v_mfma_f32_16x16x32_bf16 v[30:33], v[144:147], v[202:205], v[30:33]
	v_mfma_f32_16x16x32_bf16 v[26:29], v[178:181], v[202:205], v[26:29]
	s_waitcnt lgkmcnt(1)
	v_mfma_f32_16x16x32_bf16 v[14:17], v[144:147], v[210:213], v[14:17]
	v_mfma_f32_16x16x32_bf16 v[10:13], v[178:181], v[210:213], v[10:13]
	v_mfma_f32_16x16x32_bf16 v[62:65], v[148:151], v[190:193], v[62:65]
	v_mfma_f32_16x16x32_bf16 v[58:61], v[182:185], v[190:193], v[58:61]
	v_mfma_f32_16x16x32_bf16 v[46:49], v[148:151], v[198:201], v[46:49]
	v_mfma_f32_16x16x32_bf16 v[42:45], v[182:185], v[198:201], v[42:45]
	v_mfma_f32_16x16x32_bf16 v[30:33], v[148:151], v[206:209], v[30:33]
	v_mfma_f32_16x16x32_bf16 v[26:29], v[182:185], v[206:209], v[26:29]
	s_waitcnt lgkmcnt(0)
	v_mfma_f32_16x16x32_bf16 v[14:17], v[148:151], v[214:217], v[14:17]
	v_mfma_f32_16x16x32_bf16 v[10:13], v[182:185], v[214:217], v[10:13]
	s_barrier
	s_mov_b32 m0, s34
	s_nop 0
	global_load_lds_dwordx4 v243, s[8:9]
	s_mov_b32 m0, s35
	s_nop 0
	global_load_lds_dwordx4 v242, s[8:9]
	s_waitcnt vmcnt(6)
	s_barrier
	v_mfma_f32_16x16x32_bf16 v[54:57], v[218:221], v[186:189], v[54:57]
	v_mfma_f32_16x16x32_bf16 v[50:53], v[226:229], v[186:189], v[50:53]
	v_mfma_f32_16x16x32_bf16 v[38:41], v[218:221], v[194:197], v[38:41]
	v_mfma_f32_16x16x32_bf16 v[34:37], v[226:229], v[194:197], v[34:37]
	v_mfma_f32_16x16x32_bf16 v[22:25], v[218:221], v[202:205], v[22:25]
	v_mfma_f32_16x16x32_bf16 v[18:21], v[226:229], v[202:205], v[18:21]
	v_mfma_f32_16x16x32_bf16 v[6:9], v[218:221], v[210:213], v[6:9]
	v_mfma_f32_16x16x32_bf16 v[2:5], v[226:229], v[210:213], v[2:5]
	v_mfma_f32_16x16x32_bf16 v[54:57], v[222:225], v[190:193], v[54:57]
	v_mfma_f32_16x16x32_bf16 v[50:53], v[230:233], v[190:193], v[50:53]
	v_mfma_f32_16x16x32_bf16 v[38:41], v[222:225], v[198:201], v[38:41]
	v_mfma_f32_16x16x32_bf16 v[34:37], v[230:233], v[198:201], v[34:37]
	v_mfma_f32_16x16x32_bf16 v[22:25], v[222:225], v[206:209], v[22:25]
	v_mfma_f32_16x16x32_bf16 v[18:21], v[230:233], v[206:209], v[18:21]
	v_mfma_f32_16x16x32_bf16 v[6:9], v[222:225], v[214:217], v[6:9]
	v_mfma_f32_16x16x32_bf16 v[2:5], v[230:233], v[214:217], v[2:5]
	s_barrier
	ds_read_b128 v[144:147], v169
	ds_read_b128 v[148:151], v170
	ds_read_b128 v[178:181], v171
	ds_read_b128 v[182:185], v172
	s_mov_b32 m0, s38
	ds_read_b128 v[186:189], v158 offset:32768
	ds_read_b128 v[190:193], v158 offset:33792
	ds_read_b128 v[194:197], v158 offset:34816
	ds_read_b128 v[198:201], v158 offset:35840
	ds_read_b128 v[202:205], v158 offset:36864
	ds_read_b128 v[206:209], v158 offset:37888
	ds_read_b128 v[210:213], v158 offset:38912
	ds_read_b128 v[214:217], v158 offset:39936
	global_load_lds_dwordx4 v243, s[2:3]
	s_mov_b32 m0, s39
	s_nop 0
	global_load_lds_dwordx4 v242, s[2:3]
	s_waitcnt lgkmcnt(8)
	s_barrier
	s_waitcnt lgkmcnt(7)
	v_mfma_f32_16x16x32_bf16 v[126:129], v[144:147], v[186:189], v[126:129]
	v_mfma_f32_16x16x32_bf16 v[122:125], v[178:181], v[186:189], v[122:125]
	s_waitcnt lgkmcnt(5)
	v_mfma_f32_16x16x32_bf16 v[110:113], v[144:147], v[194:197], v[110:113]
	v_mfma_f32_16x16x32_bf16 v[106:109], v[178:181], v[194:197], v[106:109]
	s_waitcnt lgkmcnt(3)
	v_mfma_f32_16x16x32_bf16 v[94:97], v[144:147], v[202:205], v[94:97]
	v_mfma_f32_16x16x32_bf16 v[90:93], v[178:181], v[202:205], v[90:93]
	s_waitcnt lgkmcnt(1)
	v_mfma_f32_16x16x32_bf16 v[78:81], v[144:147], v[210:213], v[78:81]
	v_mfma_f32_16x16x32_bf16 v[74:77], v[178:181], v[210:213], v[74:77]
	v_mfma_f32_16x16x32_bf16 v[126:129], v[148:151], v[190:193], v[126:129]
	v_mfma_f32_16x16x32_bf16 v[122:125], v[182:185], v[190:193], v[122:125]
	v_mfma_f32_16x16x32_bf16 v[110:113], v[148:151], v[198:201], v[110:113]
	v_mfma_f32_16x16x32_bf16 v[106:109], v[182:185], v[198:201], v[106:109]
	v_mfma_f32_16x16x32_bf16 v[94:97], v[148:151], v[206:209], v[94:97]
	v_mfma_f32_16x16x32_bf16 v[90:93], v[182:185], v[206:209], v[90:93]
	s_waitcnt lgkmcnt(0)
	v_mfma_f32_16x16x32_bf16 v[78:81], v[148:151], v[214:217], v[78:81]
	v_mfma_f32_16x16x32_bf16 v[74:77], v[182:185], v[214:217], v[74:77]
	s_barrier
	s_sub_u32 m0, s41, 0x80
	ds_read_b128 v[218:221], v173
	ds_read_b128 v[222:225], v174
	ds_read_b128 v[226:229], v175
	ds_read_b128 v[230:233], v176
	global_load_lds_dwordx4 v130, s[8:9] offset:128
	s_sub_u32 m0, s42, 0x80
	s_nop 0
	global_load_lds_dwordx4 v132, s[8:9] offset:128
	s_barrier
	s_waitcnt lgkmcnt(3)
	v_mfma_f32_16x16x32_bf16 v[118:121], v[218:221], v[186:189], v[118:121]
	s_waitcnt lgkmcnt(1)
	v_mfma_f32_16x16x32_bf16 v[114:117], v[226:229], v[186:189], v[114:117]
	v_mfma_f32_16x16x32_bf16 v[102:105], v[218:221], v[194:197], v[102:105]
	v_mfma_f32_16x16x32_bf16 v[98:101], v[226:229], v[194:197], v[98:101]
	v_mfma_f32_16x16x32_bf16 v[86:89], v[218:221], v[202:205], v[86:89]
	v_mfma_f32_16x16x32_bf16 v[82:85], v[226:229], v[202:205], v[82:85]
	v_mfma_f32_16x16x32_bf16 v[70:73], v[218:221], v[210:213], v[70:73]
	v_mfma_f32_16x16x32_bf16 v[66:69], v[226:229], v[210:213], v[66:69]
	v_mfma_f32_16x16x32_bf16 v[118:121], v[222:225], v[190:193], v[118:121]
	s_waitcnt lgkmcnt(0)
	v_mfma_f32_16x16x32_bf16 v[114:117], v[230:233], v[190:193], v[114:117]
	v_mfma_f32_16x16x32_bf16 v[102:105], v[222:225], v[198:201], v[102:105]
	v_mfma_f32_16x16x32_bf16 v[98:101], v[230:233], v[198:201], v[98:101]
	v_mfma_f32_16x16x32_bf16 v[86:89], v[222:225], v[206:209], v[86:89]
	v_mfma_f32_16x16x32_bf16 v[82:85], v[230:233], v[206:209], v[82:85]
	v_mfma_f32_16x16x32_bf16 v[70:73], v[222:225], v[214:217], v[70:73]
	v_mfma_f32_16x16x32_bf16 v[66:69], v[230:233], v[214:217], v[66:69]
	s_sub_u32 m0, s43, 0x80
	s_barrier
	ds_read_b128 v[186:189], v158 offset:49152
	ds_read_b128 v[190:193], v158 offset:50176
	ds_read_b128 v[194:197], v158 offset:51200
	ds_read_b128 v[198:201], v158 offset:52224
	ds_read_b128 v[202:205], v158 offset:53248
	ds_read_b128 v[206:209], v158 offset:54272
	ds_read_b128 v[210:213], v158 offset:55296
	ds_read_b128 v[214:217], v158 offset:56320
	global_load_lds_dwordx4 v130, s[2:3] offset:128
	s_sub_u32 m0, s48, 0x80
	s_nop 0
	global_load_lds_dwordx4 v132, s[2:3] offset:128
	s_barrier
	s_waitcnt lgkmcnt(7)
	v_mfma_f32_16x16x32_bf16 v[62:65], v[144:147], v[186:189], v[62:65]
	v_mfma_f32_16x16x32_bf16 v[58:61], v[178:181], v[186:189], v[58:61]
	s_waitcnt lgkmcnt(5)
	v_mfma_f32_16x16x32_bf16 v[46:49], v[144:147], v[194:197], v[46:49]
	v_mfma_f32_16x16x32_bf16 v[42:45], v[178:181], v[194:197], v[42:45]
	s_waitcnt lgkmcnt(3)
	v_mfma_f32_16x16x32_bf16 v[30:33], v[144:147], v[202:205], v[30:33]
	v_mfma_f32_16x16x32_bf16 v[26:29], v[178:181], v[202:205], v[26:29]
	s_waitcnt lgkmcnt(1)
	v_mfma_f32_16x16x32_bf16 v[14:17], v[144:147], v[210:213], v[14:17]
	v_mfma_f32_16x16x32_bf16 v[10:13], v[178:181], v[210:213], v[10:13]
	v_mfma_f32_16x16x32_bf16 v[62:65], v[148:151], v[190:193], v[62:65]
	v_mfma_f32_16x16x32_bf16 v[58:61], v[182:185], v[190:193], v[58:61]
	v_mfma_f32_16x16x32_bf16 v[46:49], v[148:151], v[198:201], v[46:49]
	v_mfma_f32_16x16x32_bf16 v[42:45], v[182:185], v[198:201], v[42:45]
	v_mfma_f32_16x16x32_bf16 v[30:33], v[148:151], v[206:209], v[30:33]
	v_mfma_f32_16x16x32_bf16 v[26:29], v[182:185], v[206:209], v[26:29]
	s_waitcnt lgkmcnt(0)
	v_mfma_f32_16x16x32_bf16 v[14:17], v[148:151], v[214:217], v[14:17]
	v_mfma_f32_16x16x32_bf16 v[10:13], v[182:185], v[214:217], v[10:13]
	s_barrier
	s_sub_u32 m0, s49, 0x80
	s_nop 0
	global_load_lds_dwordx4 v243, s[8:9] offset:128
	s_sub_u32 m0, s50, 0x80
	s_nop 0
	global_load_lds_dwordx4 v242, s[8:9] offset:128
	s_waitcnt vmcnt(6)
	s_barrier
	v_mfma_f32_16x16x32_bf16 v[54:57], v[218:221], v[186:189], v[54:57]
	v_mfma_f32_16x16x32_bf16 v[50:53], v[226:229], v[186:189], v[50:53]
	v_mfma_f32_16x16x32_bf16 v[38:41], v[218:221], v[194:197], v[38:41]
	v_mfma_f32_16x16x32_bf16 v[34:37], v[226:229], v[194:197], v[34:37]
	v_mfma_f32_16x16x32_bf16 v[22:25], v[218:221], v[202:205], v[22:25]
	v_mfma_f32_16x16x32_bf16 v[18:21], v[226:229], v[202:205], v[18:21]
	v_mfma_f32_16x16x32_bf16 v[6:9], v[218:221], v[210:213], v[6:9]
	v_mfma_f32_16x16x32_bf16 v[2:5], v[226:229], v[210:213], v[2:5]
	v_mfma_f32_16x16x32_bf16 v[54:57], v[222:225], v[190:193], v[54:57]
	v_mfma_f32_16x16x32_bf16 v[50:53], v[230:233], v[190:193], v[50:53]
	v_mfma_f32_16x16x32_bf16 v[38:41], v[222:225], v[198:201], v[38:41]
	v_mfma_f32_16x16x32_bf16 v[34:37], v[230:233], v[198:201], v[34:37]
	v_mfma_f32_16x16x32_bf16 v[22:25], v[222:225], v[206:209], v[22:25]
	v_mfma_f32_16x16x32_bf16 v[18:21], v[230:233], v[206:209], v[18:21]
	v_mfma_f32_16x16x32_bf16 v[6:9], v[222:225], v[214:217], v[6:9]
	v_mfma_f32_16x16x32_bf16 v[2:5], v[230:233], v[214:217], v[2:5]
	s_add_u32 s6, s6, 0x100
	s_addc_u32 s7, s7, 0
	s_add_u32 s10, s10, 0x100
	s_addc_u32 s11, s11, 0
	s_cmp_ge_i32 s14, s51
	s_mov_b32 s2, s14
	s_barrier
	s_cbranch_scc0 .LBB0_236

.LBB0_997:
	ds_read_b128 v[142:145], v168
	ds_read_b128 v[146:149], v169
	ds_read_b128 v[150:153], v170
	ds_read_b128 v[154:157], v171
	s_add_i32 s57, s2, 2
	s_add_u32 s26, s24, 0x80
	s_addc_u32 s3, s25, 0
	s_cmp_eq_u32 s46, s2
	s_cselect_b32 s2, s10, s26
	s_cselect_b32 s3, s11, s3
	s_cselect_b32 s27, s1, s37
	s_cselect_b32 s26, s0, s36
	s_mov_b32 m0, s51
	ds_read_b128 v[186:189], v166
	ds_read_b128 v[190:193], v166 offset:1024
	ds_read_b128 v[194:197], v166 offset:2048
	ds_read_b128 v[198:201], v166 offset:3072
	ds_read_b128 v[202:205], v166 offset:4096
	ds_read_b128 v[206:209], v166 offset:5120
	ds_read_b128 v[210:213], v166 offset:6144
	ds_read_b128 v[214:217], v166 offset:7168
	global_load_lds_dwordx4 v134, s[24:25]
	s_mov_b32 m0, s52
	s_nop 0
	global_load_lds_dwordx4 v136, s[24:25]
	s_waitcnt lgkmcnt(8)
	s_barrier
	s_waitcnt lgkmcnt(7)
	v_mfma_f32_16x16x32_bf16 v[126:129], v[142:145], v[186:189], v[126:129]
	v_mfma_f32_16x16x32_bf16 v[122:125], v[150:153], v[186:189], v[122:125]
	s_waitcnt lgkmcnt(5)
	v_mfma_f32_16x16x32_bf16 v[110:113], v[142:145], v[194:197], v[110:113]
	v_mfma_f32_16x16x32_bf16 v[106:109], v[150:153], v[194:197], v[106:109]
	s_waitcnt lgkmcnt(3)
	v_mfma_f32_16x16x32_bf16 v[94:97], v[142:145], v[202:205], v[94:97]
	v_mfma_f32_16x16x32_bf16 v[90:93], v[150:153], v[202:205], v[90:93]
	s_waitcnt lgkmcnt(1)
	v_mfma_f32_16x16x32_bf16 v[78:81], v[142:145], v[210:213], v[78:81]
	v_mfma_f32_16x16x32_bf16 v[74:77], v[150:153], v[210:213], v[74:77]
	v_mfma_f32_16x16x32_bf16 v[126:129], v[146:149], v[190:193], v[126:129]
	v_mfma_f32_16x16x32_bf16 v[122:125], v[154:157], v[190:193], v[122:125]
	v_mfma_f32_16x16x32_bf16 v[110:113], v[146:149], v[198:201], v[110:113]
	v_mfma_f32_16x16x32_bf16 v[106:109], v[154:157], v[198:201], v[106:109]
	v_mfma_f32_16x16x32_bf16 v[94:97], v[146:149], v[206:209], v[94:97]
	v_mfma_f32_16x16x32_bf16 v[90:93], v[154:157], v[206:209], v[90:93]
	s_waitcnt lgkmcnt(0)
	v_mfma_f32_16x16x32_bf16 v[78:81], v[146:149], v[214:217], v[78:81]
	v_mfma_f32_16x16x32_bf16 v[74:77], v[154:157], v[214:217], v[74:77]
	s_barrier
	s_mov_b32 m0, s29
	ds_read_b128 v[218:221], v172
	ds_read_b128 v[222:225], v173
	ds_read_b128 v[226:229], v174
	ds_read_b128 v[230:233], v175
	global_load_lds_dwordx4 v130, s[26:27]
	s_mov_b32 m0, s30
	s_nop 0
	global_load_lds_dwordx4 v132, s[26:27]
	s_barrier
	s_waitcnt lgkmcnt(3)
	v_mfma_f32_16x16x32_bf16 v[118:121], v[218:221], v[186:189], v[118:121]
	s_waitcnt lgkmcnt(1)
	v_mfma_f32_16x16x32_bf16 v[114:117], v[226:229], v[186:189], v[114:117]
	v_mfma_f32_16x16x32_bf16 v[102:105], v[218:221], v[194:197], v[102:105]
	v_mfma_f32_16x16x32_bf16 v[98:101], v[226:229], v[194:197], v[98:101]
	v_mfma_f32_16x16x32_bf16 v[86:89], v[218:221], v[202:205], v[86:89]
	v_mfma_f32_16x16x32_bf16 v[82:85], v[226:229], v[202:205], v[82:85]
	v_mfma_f32_16x16x32_bf16 v[70:73], v[218:221], v[210:213], v[70:73]
	v_mfma_f32_16x16x32_bf16 v[66:69], v[226:229], v[210:213], v[66:69]
	v_mfma_f32_16x16x32_bf16 v[118:121], v[222:225], v[190:193], v[118:121]
	s_waitcnt lgkmcnt(0)
	v_mfma_f32_16x16x32_bf16 v[114:117], v[230:233], v[190:193], v[114:117]
	v_mfma_f32_16x16x32_bf16 v[102:105], v[222:225], v[198:201], v[102:105]
	v_mfma_f32_16x16x32_bf16 v[98:101], v[230:233], v[198:201], v[98:101]
	v_mfma_f32_16x16x32_bf16 v[86:89], v[222:225], v[206:209], v[86:89]
	v_mfma_f32_16x16x32_bf16 v[82:85], v[230:233], v[206:209], v[82:85]
	v_mfma_f32_16x16x32_bf16 v[70:73], v[222:225], v[214:217], v[70:73]
	v_mfma_f32_16x16x32_bf16 v[66:69], v[230:233], v[214:217], v[66:69]
	s_mov_b32 m0, s28
	s_barrier
	ds_read_b128 v[186:189], v166 offset:16384
	ds_read_b128 v[190:193], v166 offset:17408
	ds_read_b128 v[194:197], v166 offset:18432
	ds_read_b128 v[198:201], v166 offset:19456
	ds_read_b128 v[202:205], v166 offset:20480
	ds_read_b128 v[206:209], v166 offset:21504
	ds_read_b128 v[210:213], v166 offset:22528
	ds_read_b128 v[214:217], v166 offset:23552
	global_load_lds_dwordx4 v130, s[2:3]
	s_mov_b32 m0, s31
	s_nop 0
	global_load_lds_dwordx4 v132, s[2:3]
	s_barrier
	s_waitcnt lgkmcnt(7)
	v_mfma_f32_16x16x32_bf16 v[62:65], v[142:145], v[186:189], v[62:65]
	v_mfma_f32_16x16x32_bf16 v[58:61], v[150:153], v[186:189], v[58:61]
	s_waitcnt lgkmcnt(5)
	v_mfma_f32_16x16x32_bf16 v[46:49], v[142:145], v[194:197], v[46:49]
	v_mfma_f32_16x16x32_bf16 v[42:45], v[150:153], v[194:197], v[42:45]
	s_waitcnt lgkmcnt(3)
	v_mfma_f32_16x16x32_bf16 v[30:33], v[142:145], v[202:205], v[30:33]
	v_mfma_f32_16x16x32_bf16 v[26:29], v[150:153], v[202:205], v[26:29]
	s_waitcnt lgkmcnt(1)
	v_mfma_f32_16x16x32_bf16 v[14:17], v[142:145], v[210:213], v[14:17]
	v_mfma_f32_16x16x32_bf16 v[10:13], v[150:153], v[210:213], v[10:13]
	v_mfma_f32_16x16x32_bf16 v[62:65], v[146:149], v[190:193], v[62:65]
	v_mfma_f32_16x16x32_bf16 v[58:61], v[154:157], v[190:193], v[58:61]
	v_mfma_f32_16x16x32_bf16 v[46:49], v[146:149], v[198:201], v[46:49]
	v_mfma_f32_16x16x32_bf16 v[42:45], v[154:157], v[198:201], v[42:45]
	v_mfma_f32_16x16x32_bf16 v[30:33], v[146:149], v[206:209], v[30:33]
	v_mfma_f32_16x16x32_bf16 v[26:29], v[154:157], v[206:209], v[26:29]
	s_waitcnt lgkmcnt(0)
	v_mfma_f32_16x16x32_bf16 v[14:17], v[146:149], v[214:217], v[14:17]
	v_mfma_f32_16x16x32_bf16 v[10:13], v[154:157], v[214:217], v[10:13]
	s_barrier
	s_mov_b32 m0, s33
	s_nop 0
	global_load_lds_dwordx4 v243, s[26:27]
	s_mov_b32 m0, s34
	s_nop 0
	global_load_lds_dwordx4 v242, s[26:27]
	s_waitcnt vmcnt(6)
	s_barrier
	v_mfma_f32_16x16x32_bf16 v[54:57], v[218:221], v[186:189], v[54:57]
	v_mfma_f32_16x16x32_bf16 v[50:53], v[226:229], v[186:189], v[50:53]
	v_mfma_f32_16x16x32_bf16 v[38:41], v[218:221], v[194:197], v[38:41]
	v_mfma_f32_16x16x32_bf16 v[34:37], v[226:229], v[194:197], v[34:37]
	v_mfma_f32_16x16x32_bf16 v[22:25], v[218:221], v[202:205], v[22:25]
	v_mfma_f32_16x16x32_bf16 v[18:21], v[226:229], v[202:205], v[18:21]
	v_mfma_f32_16x16x32_bf16 v[6:9], v[218:221], v[210:213], v[6:9]
	v_mfma_f32_16x16x32_bf16 v[2:5], v[226:229], v[210:213], v[2:5]
	v_mfma_f32_16x16x32_bf16 v[54:57], v[222:225], v[190:193], v[54:57]
	v_mfma_f32_16x16x32_bf16 v[50:53], v[230:233], v[190:193], v[50:53]
	v_mfma_f32_16x16x32_bf16 v[38:41], v[222:225], v[198:201], v[38:41]
	v_mfma_f32_16x16x32_bf16 v[34:37], v[230:233], v[198:201], v[34:37]
	v_mfma_f32_16x16x32_bf16 v[22:25], v[222:225], v[206:209], v[22:25]
	v_mfma_f32_16x16x32_bf16 v[18:21], v[230:233], v[206:209], v[18:21]
	v_mfma_f32_16x16x32_bf16 v[6:9], v[222:225], v[214:217], v[6:9]
	v_mfma_f32_16x16x32_bf16 v[2:5], v[230:233], v[214:217], v[2:5]
	s_barrier
	ds_read_b128 v[142:145], v176
	ds_read_b128 v[146:149], v177
	ds_read_b128 v[150:153], v178
	ds_read_b128 v[154:157], v179
	s_mov_b32 m0, s35
	ds_read_b128 v[186:189], v166 offset:32768
	ds_read_b128 v[190:193], v166 offset:33792
	ds_read_b128 v[194:197], v166 offset:34816
	ds_read_b128 v[198:201], v166 offset:35840
	ds_read_b128 v[202:205], v166 offset:36864
	ds_read_b128 v[206:209], v166 offset:37888
	ds_read_b128 v[210:213], v166 offset:38912
	ds_read_b128 v[214:217], v166 offset:39936
	global_load_lds_dwordx4 v243, s[2:3]
	s_mov_b32 m0, s38
	s_nop 0
	global_load_lds_dwordx4 v242, s[2:3]
	s_waitcnt lgkmcnt(8)
	s_barrier
	s_waitcnt lgkmcnt(7)
	v_mfma_f32_16x16x32_bf16 v[126:129], v[142:145], v[186:189], v[126:129]
	v_mfma_f32_16x16x32_bf16 v[122:125], v[150:153], v[186:189], v[122:125]
	s_waitcnt lgkmcnt(5)
	v_mfma_f32_16x16x32_bf16 v[110:113], v[142:145], v[194:197], v[110:113]
	v_mfma_f32_16x16x32_bf16 v[106:109], v[150:153], v[194:197], v[106:109]
	s_waitcnt lgkmcnt(3)
	v_mfma_f32_16x16x32_bf16 v[94:97], v[142:145], v[202:205], v[94:97]
	v_mfma_f32_16x16x32_bf16 v[90:93], v[150:153], v[202:205], v[90:93]
	s_waitcnt lgkmcnt(1)
	v_mfma_f32_16x16x32_bf16 v[78:81], v[142:145], v[210:213], v[78:81]
	v_mfma_f32_16x16x32_bf16 v[74:77], v[150:153], v[210:213], v[74:77]
	v_mfma_f32_16x16x32_bf16 v[126:129], v[146:149], v[190:193], v[126:129]
	v_mfma_f32_16x16x32_bf16 v[122:125], v[154:157], v[190:193], v[122:125]
	v_mfma_f32_16x16x32_bf16 v[110:113], v[146:149], v[198:201], v[110:113]
	v_mfma_f32_16x16x32_bf16 v[106:109], v[154:157], v[198:201], v[106:109]
	v_mfma_f32_16x16x32_bf16 v[94:97], v[146:149], v[206:209], v[94:97]
	v_mfma_f32_16x16x32_bf16 v[90:93], v[154:157], v[206:209], v[90:93]
	s_waitcnt lgkmcnt(0)
	v_mfma_f32_16x16x32_bf16 v[78:81], v[146:149], v[214:217], v[78:81]
	v_mfma_f32_16x16x32_bf16 v[74:77], v[154:157], v[214:217], v[74:77]
	s_barrier
	s_sub_u32 m0, s39, 0x80
	ds_read_b128 v[218:221], v180
	ds_read_b128 v[222:225], v181
	ds_read_b128 v[226:229], v182
	ds_read_b128 v[230:233], v183
	global_load_lds_dwordx4 v130, s[26:27] offset:128
	s_sub_u32 m0, s40, 0x80
	s_nop 0
	global_load_lds_dwordx4 v132, s[26:27] offset:128
	s_barrier
	s_waitcnt lgkmcnt(3)
	v_mfma_f32_16x16x32_bf16 v[118:121], v[218:221], v[186:189], v[118:121]
	s_waitcnt lgkmcnt(1)
	v_mfma_f32_16x16x32_bf16 v[114:117], v[226:229], v[186:189], v[114:117]
	v_mfma_f32_16x16x32_bf16 v[102:105], v[218:221], v[194:197], v[102:105]
	v_mfma_f32_16x16x32_bf16 v[98:101], v[226:229], v[194:197], v[98:101]
	v_mfma_f32_16x16x32_bf16 v[86:89], v[218:221], v[202:205], v[86:89]
	v_mfma_f32_16x16x32_bf16 v[82:85], v[226:229], v[202:205], v[82:85]
	v_mfma_f32_16x16x32_bf16 v[70:73], v[218:221], v[210:213], v[70:73]
	v_mfma_f32_16x16x32_bf16 v[66:69], v[226:229], v[210:213], v[66:69]
	v_mfma_f32_16x16x32_bf16 v[118:121], v[222:225], v[190:193], v[118:121]
	s_waitcnt lgkmcnt(0)
	v_mfma_f32_16x16x32_bf16 v[114:117], v[230:233], v[190:193], v[114:117]
	v_mfma_f32_16x16x32_bf16 v[102:105], v[222:225], v[198:201], v[102:105]
	v_mfma_f32_16x16x32_bf16 v[98:101], v[230:233], v[198:201], v[98:101]
	v_mfma_f32_16x16x32_bf16 v[86:89], v[222:225], v[206:209], v[86:89]
	v_mfma_f32_16x16x32_bf16 v[82:85], v[230:233], v[206:209], v[82:85]
	v_mfma_f32_16x16x32_bf16 v[70:73], v[222:225], v[214:217], v[70:73]
	v_mfma_f32_16x16x32_bf16 v[66:69], v[230:233], v[214:217], v[66:69]
	s_sub_u32 m0, s41, 0x80
	s_barrier
	ds_read_b128 v[186:189], v166 offset:49152
	ds_read_b128 v[190:193], v166 offset:50176
	ds_read_b128 v[194:197], v166 offset:51200
	ds_read_b128 v[198:201], v166 offset:52224
	ds_read_b128 v[202:205], v166 offset:53248
	ds_read_b128 v[206:209], v166 offset:54272
	ds_read_b128 v[210:213], v166 offset:55296
	ds_read_b128 v[214:217], v166 offset:56320
	global_load_lds_dwordx4 v130, s[2:3] offset:128
	s_sub_u32 m0, s42, 0x80
	s_nop 0
	global_load_lds_dwordx4 v132, s[2:3] offset:128
	s_barrier
	s_waitcnt lgkmcnt(7)
	v_mfma_f32_16x16x32_bf16 v[62:65], v[142:145], v[186:189], v[62:65]
	v_mfma_f32_16x16x32_bf16 v[58:61], v[150:153], v[186:189], v[58:61]
	s_waitcnt lgkmcnt(5)
	v_mfma_f32_16x16x32_bf16 v[46:49], v[142:145], v[194:197], v[46:49]
	v_mfma_f32_16x16x32_bf16 v[42:45], v[150:153], v[194:197], v[42:45]
	s_waitcnt lgkmcnt(3)
	v_mfma_f32_16x16x32_bf16 v[30:33], v[142:145], v[202:205], v[30:33]
	v_mfma_f32_16x16x32_bf16 v[26:29], v[150:153], v[202:205], v[26:29]
	s_waitcnt lgkmcnt(1)
	v_mfma_f32_16x16x32_bf16 v[14:17], v[142:145], v[210:213], v[14:17]
	v_mfma_f32_16x16x32_bf16 v[10:13], v[150:153], v[210:213], v[10:13]
	v_mfma_f32_16x16x32_bf16 v[62:65], v[146:149], v[190:193], v[62:65]
	v_mfma_f32_16x16x32_bf16 v[58:61], v[154:157], v[190:193], v[58:61]
	v_mfma_f32_16x16x32_bf16 v[46:49], v[146:149], v[198:201], v[46:49]
	v_mfma_f32_16x16x32_bf16 v[42:45], v[154:157], v[198:201], v[42:45]
	v_mfma_f32_16x16x32_bf16 v[30:33], v[146:149], v[206:209], v[30:33]
	v_mfma_f32_16x16x32_bf16 v[26:29], v[154:157], v[206:209], v[26:29]
	s_waitcnt lgkmcnt(0)
	v_mfma_f32_16x16x32_bf16 v[14:17], v[146:149], v[214:217], v[14:17]
	v_mfma_f32_16x16x32_bf16 v[10:13], v[154:157], v[214:217], v[10:13]
	s_barrier
	s_sub_u32 m0, s43, 0x80
	s_nop 0
	global_load_lds_dwordx4 v243, s[26:27] offset:128
	s_sub_u32 m0, s44, 0x80
	s_nop 0
	global_load_lds_dwordx4 v242, s[26:27] offset:128
	s_waitcnt vmcnt(6)
	s_barrier
	v_mfma_f32_16x16x32_bf16 v[54:57], v[218:221], v[186:189], v[54:57]
	v_mfma_f32_16x16x32_bf16 v[50:53], v[226:229], v[186:189], v[50:53]
	v_mfma_f32_16x16x32_bf16 v[38:41], v[218:221], v[194:197], v[38:41]
	v_mfma_f32_16x16x32_bf16 v[34:37], v[226:229], v[194:197], v[34:37]
	v_mfma_f32_16x16x32_bf16 v[22:25], v[218:221], v[202:205], v[22:25]
	v_mfma_f32_16x16x32_bf16 v[18:21], v[226:229], v[202:205], v[18:21]
	v_mfma_f32_16x16x32_bf16 v[6:9], v[218:221], v[210:213], v[6:9]
	v_mfma_f32_16x16x32_bf16 v[2:5], v[226:229], v[210:213], v[2:5]
	v_mfma_f32_16x16x32_bf16 v[54:57], v[222:225], v[190:193], v[54:57]
	v_mfma_f32_16x16x32_bf16 v[50:53], v[230:233], v[190:193], v[50:53]
	v_mfma_f32_16x16x32_bf16 v[38:41], v[222:225], v[198:201], v[38:41]
	v_mfma_f32_16x16x32_bf16 v[34:37], v[230:233], v[198:201], v[34:37]
	v_mfma_f32_16x16x32_bf16 v[22:25], v[222:225], v[206:209], v[22:25]
	v_mfma_f32_16x16x32_bf16 v[18:21], v[230:233], v[206:209], v[18:21]
	v_mfma_f32_16x16x32_bf16 v[6:9], v[222:225], v[214:217], v[6:9]
	v_mfma_f32_16x16x32_bf16 v[2:5], v[230:233], v[214:217], v[2:5]
	s_add_u32 s24, s24, 0x100
	s_addc_u32 s25, s25, 0
	s_add_u32 s36, s36, 0x100
	s_addc_u32 s37, s37, 0
	s_cmp_ge_i32 s57, s45
	s_mov_b32 s2, s57
	s_barrier
	s_cbranch_scc0 .LBB0_997

.LBB0_1104:
	ds_read_b128 v[122:125], v185
	ds_read_b128 v[126:129], v186
	ds_read_b128 v[138:141], v187
	ds_read_b128 v[142:145], v188
	s_add_i32 s36, s2, 2
	s_add_u32 s26, s0, 0x80
	s_addc_u32 s3, s1, 0
	s_cmp_eq_u32 s58, s2
	s_cselect_b32 s2, s8, s26
	s_cselect_b32 s3, s9, s3
	s_cselect_b32 s27, s55, s29
	s_cselect_b32 s26, s54, s28
	s_mov_b32 m0, s61
	ds_read_b128 v[146:149], v183
	ds_read_b128 v[150:153], v183 offset:1024
	ds_read_b128 v[154:157], v183 offset:2048
	ds_read_b128 v[158:161], v183 offset:3072
	ds_read_b128 v[176:179], v183 offset:4096
	ds_read_b128 v[202:205], v183 offset:5120
	ds_read_b128 v[206:209], v183 offset:6144
	ds_read_b128 v[210:213], v183 offset:7168
	global_load_lds_dwordx4 v168, s[0:1]
	s_mov_b32 m0, s62
	s_nop 0
	global_load_lds_dwordx4 v170, s[0:1]
	s_waitcnt lgkmcnt(8)
	s_barrier
	s_waitcnt lgkmcnt(7)
	v_mfma_f32_16x16x32_bf16 v[134:137], v[122:125], v[146:149], v[134:137]
	v_mfma_f32_16x16x32_bf16 v[118:121], v[138:141], v[146:149], v[118:121]
	s_waitcnt lgkmcnt(5)
	v_mfma_f32_16x16x32_bf16 v[110:113], v[122:125], v[154:157], v[110:113]
	v_mfma_f32_16x16x32_bf16 v[102:105], v[138:141], v[154:157], v[102:105]
	s_waitcnt lgkmcnt(3)
	v_mfma_f32_16x16x32_bf16 v[94:97], v[122:125], v[176:179], v[94:97]
	v_mfma_f32_16x16x32_bf16 v[86:89], v[138:141], v[176:179], v[86:89]
	s_waitcnt lgkmcnt(1)
	v_mfma_f32_16x16x32_bf16 v[78:81], v[122:125], v[206:209], v[78:81]
	v_mfma_f32_16x16x32_bf16 v[70:73], v[138:141], v[206:209], v[70:73]
	v_mfma_f32_16x16x32_bf16 v[134:137], v[126:129], v[150:153], v[134:137]
	v_mfma_f32_16x16x32_bf16 v[118:121], v[142:145], v[150:153], v[118:121]
	v_mfma_f32_16x16x32_bf16 v[110:113], v[126:129], v[158:161], v[110:113]
	v_mfma_f32_16x16x32_bf16 v[102:105], v[142:145], v[158:161], v[102:105]
	v_mfma_f32_16x16x32_bf16 v[94:97], v[126:129], v[202:205], v[94:97]
	v_mfma_f32_16x16x32_bf16 v[86:89], v[142:145], v[202:205], v[86:89]
	s_waitcnt lgkmcnt(0)
	v_mfma_f32_16x16x32_bf16 v[78:81], v[126:129], v[210:213], v[78:81]
	v_mfma_f32_16x16x32_bf16 v[70:73], v[142:145], v[210:213], v[70:73]
	s_barrier
	s_mov_b32 m0, s35
	ds_read_b128 v[214:217], v189
	ds_read_b128 v[218:221], v190
	ds_read_b128 v[222:225], v191
	ds_read_b128 v[226:229], v192
	global_load_lds_dwordx4 v166, s[26:27]
	s_mov_b32 m0, s38
	s_nop 0
	global_load_lds_dwordx4 v164, s[26:27]
	s_barrier
	s_waitcnt lgkmcnt(3)
	v_mfma_f32_16x16x32_bf16 v[130:133], v[214:217], v[146:149], v[130:133]
	s_waitcnt lgkmcnt(1)
	v_mfma_f32_16x16x32_bf16 v[114:117], v[222:225], v[146:149], v[114:117]
	v_mfma_f32_16x16x32_bf16 v[106:109], v[214:217], v[154:157], v[106:109]
	v_mfma_f32_16x16x32_bf16 v[98:101], v[222:225], v[154:157], v[98:101]
	v_mfma_f32_16x16x32_bf16 v[90:93], v[214:217], v[176:179], v[90:93]
	v_mfma_f32_16x16x32_bf16 v[82:85], v[222:225], v[176:179], v[82:85]
	v_mfma_f32_16x16x32_bf16 v[74:77], v[214:217], v[206:209], v[74:77]
	v_mfma_f32_16x16x32_bf16 v[66:69], v[222:225], v[206:209], v[66:69]
	v_mfma_f32_16x16x32_bf16 v[130:133], v[218:221], v[150:153], v[130:133]
	s_waitcnt lgkmcnt(0)
	v_mfma_f32_16x16x32_bf16 v[114:117], v[226:229], v[150:153], v[114:117]
	v_mfma_f32_16x16x32_bf16 v[106:109], v[218:221], v[158:161], v[106:109]
	v_mfma_f32_16x16x32_bf16 v[98:101], v[226:229], v[158:161], v[98:101]
	v_mfma_f32_16x16x32_bf16 v[90:93], v[218:221], v[202:205], v[90:93]
	v_mfma_f32_16x16x32_bf16 v[82:85], v[226:229], v[202:205], v[82:85]
	v_mfma_f32_16x16x32_bf16 v[74:77], v[218:221], v[210:213], v[74:77]
	v_mfma_f32_16x16x32_bf16 v[66:69], v[226:229], v[210:213], v[66:69]
	s_mov_b32 m0, s31
	s_barrier
	ds_read_b128 v[146:149], v183 offset:16384
	ds_read_b128 v[150:153], v183 offset:17408
	ds_read_b128 v[154:157], v183 offset:18432
	ds_read_b128 v[158:161], v183 offset:19456
	ds_read_b128 v[176:179], v183 offset:20480
	ds_read_b128 v[202:205], v183 offset:21504
	ds_read_b128 v[206:209], v183 offset:22528
	ds_read_b128 v[210:213], v183 offset:23552
	global_load_lds_dwordx4 v166, s[2:3]
	s_mov_b32 m0, s39
	s_nop 0
	global_load_lds_dwordx4 v164, s[2:3]
	s_barrier
	s_waitcnt lgkmcnt(7)
	v_mfma_f32_16x16x32_bf16 v[62:65], v[122:125], v[146:149], v[62:65]
	v_mfma_f32_16x16x32_bf16 v[54:57], v[138:141], v[146:149], v[54:57]
	s_waitcnt lgkmcnt(5)
	v_mfma_f32_16x16x32_bf16 v[46:49], v[122:125], v[154:157], v[46:49]
	v_mfma_f32_16x16x32_bf16 v[38:41], v[138:141], v[154:157], v[38:41]
	s_waitcnt lgkmcnt(3)
	v_mfma_f32_16x16x32_bf16 v[30:33], v[122:125], v[176:179], v[30:33]
	v_mfma_f32_16x16x32_bf16 v[22:25], v[138:141], v[176:179], v[22:25]
	s_waitcnt lgkmcnt(1)
	v_mfma_f32_16x16x32_bf16 v[14:17], v[122:125], v[206:209], v[14:17]
	v_mfma_f32_16x16x32_bf16 v[6:9], v[138:141], v[206:209], v[6:9]
	v_mfma_f32_16x16x32_bf16 v[62:65], v[126:129], v[150:153], v[62:65]
	v_mfma_f32_16x16x32_bf16 v[54:57], v[142:145], v[150:153], v[54:57]
	v_mfma_f32_16x16x32_bf16 v[46:49], v[126:129], v[158:161], v[46:49]
	v_mfma_f32_16x16x32_bf16 v[38:41], v[142:145], v[158:161], v[38:41]
	v_mfma_f32_16x16x32_bf16 v[30:33], v[126:129], v[202:205], v[30:33]
	v_mfma_f32_16x16x32_bf16 v[22:25], v[142:145], v[202:205], v[22:25]
	s_waitcnt lgkmcnt(0)
	v_mfma_f32_16x16x32_bf16 v[14:17], v[126:129], v[210:213], v[14:17]
	v_mfma_f32_16x16x32_bf16 v[6:9], v[142:145], v[210:213], v[6:9]
	s_barrier
	s_mov_b32 m0, s40
	s_nop 0
	global_load_lds_dwordx4 v240, s[26:27]
	s_mov_b32 m0, s41
	s_nop 0
	global_load_lds_dwordx4 v241, s[26:27]
	s_waitcnt vmcnt(6)
	s_barrier
	v_mfma_f32_16x16x32_bf16 v[58:61], v[214:217], v[146:149], v[58:61]
	v_mfma_f32_16x16x32_bf16 v[50:53], v[222:225], v[146:149], v[50:53]
	v_mfma_f32_16x16x32_bf16 v[42:45], v[214:217], v[154:157], v[42:45]
	v_mfma_f32_16x16x32_bf16 v[34:37], v[222:225], v[154:157], v[34:37]
	v_mfma_f32_16x16x32_bf16 v[26:29], v[214:217], v[176:179], v[26:29]
	v_mfma_f32_16x16x32_bf16 v[18:21], v[222:225], v[176:179], v[18:21]
	v_mfma_f32_16x16x32_bf16 v[10:13], v[214:217], v[206:209], v[10:13]
	v_mfma_f32_16x16x32_bf16 v[2:5], v[222:225], v[206:209], v[2:5]
	v_mfma_f32_16x16x32_bf16 v[58:61], v[218:221], v[150:153], v[58:61]
	v_mfma_f32_16x16x32_bf16 v[50:53], v[226:229], v[150:153], v[50:53]
	v_mfma_f32_16x16x32_bf16 v[42:45], v[218:221], v[158:161], v[42:45]
	v_mfma_f32_16x16x32_bf16 v[34:37], v[226:229], v[158:161], v[34:37]
	v_mfma_f32_16x16x32_bf16 v[26:29], v[218:221], v[202:205], v[26:29]
	v_mfma_f32_16x16x32_bf16 v[18:21], v[226:229], v[202:205], v[18:21]
	v_mfma_f32_16x16x32_bf16 v[10:13], v[218:221], v[210:213], v[10:13]
	v_mfma_f32_16x16x32_bf16 v[2:5], v[226:229], v[210:213], v[2:5]
	s_barrier
	ds_read_b128 v[122:125], v193
	ds_read_b128 v[126:129], v194
	ds_read_b128 v[138:141], v195
	ds_read_b128 v[142:145], v196
	s_mov_b32 m0, s42
	ds_read_b128 v[146:149], v183 offset:32768
	ds_read_b128 v[150:153], v183 offset:33792
	ds_read_b128 v[154:157], v183 offset:34816
	ds_read_b128 v[158:161], v183 offset:35840
	ds_read_b128 v[176:179], v183 offset:36864
	ds_read_b128 v[202:205], v183 offset:37888
	ds_read_b128 v[206:209], v183 offset:38912
	ds_read_b128 v[210:213], v183 offset:39936
	global_load_lds_dwordx4 v240, s[2:3]
	s_mov_b32 m0, s43
	s_nop 0
	global_load_lds_dwordx4 v241, s[2:3]
	s_waitcnt lgkmcnt(8)
	s_barrier
	s_waitcnt lgkmcnt(7)
	v_mfma_f32_16x16x32_bf16 v[134:137], v[122:125], v[146:149], v[134:137]
	v_mfma_f32_16x16x32_bf16 v[118:121], v[138:141], v[146:149], v[118:121]
	s_waitcnt lgkmcnt(5)
	v_mfma_f32_16x16x32_bf16 v[110:113], v[122:125], v[154:157], v[110:113]
	v_mfma_f32_16x16x32_bf16 v[102:105], v[138:141], v[154:157], v[102:105]
	s_waitcnt lgkmcnt(3)
	v_mfma_f32_16x16x32_bf16 v[94:97], v[122:125], v[176:179], v[94:97]
	v_mfma_f32_16x16x32_bf16 v[86:89], v[138:141], v[176:179], v[86:89]
	s_waitcnt lgkmcnt(1)
	v_mfma_f32_16x16x32_bf16 v[78:81], v[122:125], v[206:209], v[78:81]
	v_mfma_f32_16x16x32_bf16 v[70:73], v[138:141], v[206:209], v[70:73]
	v_mfma_f32_16x16x32_bf16 v[134:137], v[126:129], v[150:153], v[134:137]
	v_mfma_f32_16x16x32_bf16 v[118:121], v[142:145], v[150:153], v[118:121]
	v_mfma_f32_16x16x32_bf16 v[110:113], v[126:129], v[158:161], v[110:113]
	v_mfma_f32_16x16x32_bf16 v[102:105], v[142:145], v[158:161], v[102:105]
	v_mfma_f32_16x16x32_bf16 v[94:97], v[126:129], v[202:205], v[94:97]
	v_mfma_f32_16x16x32_bf16 v[86:89], v[142:145], v[202:205], v[86:89]
	s_waitcnt lgkmcnt(0)
	v_mfma_f32_16x16x32_bf16 v[78:81], v[126:129], v[210:213], v[78:81]
	v_mfma_f32_16x16x32_bf16 v[70:73], v[142:145], v[210:213], v[70:73]
	s_barrier
	s_sub_u32 m0, s48, 0x80
	ds_read_b128 v[214:217], v197
	ds_read_b128 v[218:221], v198
	ds_read_b128 v[222:225], v199
	ds_read_b128 v[226:229], v200
	global_load_lds_dwordx4 v166, s[26:27] offset:128
	s_sub_u32 m0, s49, 0x80
	s_nop 0
	global_load_lds_dwordx4 v164, s[26:27] offset:128
	s_barrier
	s_waitcnt lgkmcnt(3)
	v_mfma_f32_16x16x32_bf16 v[130:133], v[214:217], v[146:149], v[130:133]
	s_waitcnt lgkmcnt(1)
	v_mfma_f32_16x16x32_bf16 v[114:117], v[222:225], v[146:149], v[114:117]
	v_mfma_f32_16x16x32_bf16 v[106:109], v[214:217], v[154:157], v[106:109]
	v_mfma_f32_16x16x32_bf16 v[98:101], v[222:225], v[154:157], v[98:101]
	v_mfma_f32_16x16x32_bf16 v[90:93], v[214:217], v[176:179], v[90:93]
	v_mfma_f32_16x16x32_bf16 v[82:85], v[222:225], v[176:179], v[82:85]
	v_mfma_f32_16x16x32_bf16 v[74:77], v[214:217], v[206:209], v[74:77]
	v_mfma_f32_16x16x32_bf16 v[66:69], v[222:225], v[206:209], v[66:69]
	v_mfma_f32_16x16x32_bf16 v[130:133], v[218:221], v[150:153], v[130:133]
	s_waitcnt lgkmcnt(0)
	v_mfma_f32_16x16x32_bf16 v[114:117], v[226:229], v[150:153], v[114:117]
	v_mfma_f32_16x16x32_bf16 v[106:109], v[218:221], v[158:161], v[106:109]
	v_mfma_f32_16x16x32_bf16 v[98:101], v[226:229], v[158:161], v[98:101]
	v_mfma_f32_16x16x32_bf16 v[90:93], v[218:221], v[202:205], v[90:93]
	v_mfma_f32_16x16x32_bf16 v[82:85], v[226:229], v[202:205], v[82:85]
	v_mfma_f32_16x16x32_bf16 v[74:77], v[218:221], v[210:213], v[74:77]
	v_mfma_f32_16x16x32_bf16 v[66:69], v[226:229], v[210:213], v[66:69]
	s_sub_u32 m0, s50, 0x80
	s_barrier
	ds_read_b128 v[146:149], v183 offset:49152
	ds_read_b128 v[150:153], v183 offset:50176
	ds_read_b128 v[154:157], v183 offset:51200
	ds_read_b128 v[158:161], v183 offset:52224
	ds_read_b128 v[176:179], v183 offset:53248
	ds_read_b128 v[202:205], v183 offset:54272
	ds_read_b128 v[206:209], v183 offset:55296
	ds_read_b128 v[210:213], v183 offset:56320
	global_load_lds_dwordx4 v166, s[2:3] offset:128
	s_sub_u32 m0, s51, 0x80
	s_nop 0
	global_load_lds_dwordx4 v164, s[2:3] offset:128
	s_barrier
	s_waitcnt lgkmcnt(7)
	v_mfma_f32_16x16x32_bf16 v[62:65], v[122:125], v[146:149], v[62:65]
	v_mfma_f32_16x16x32_bf16 v[54:57], v[138:141], v[146:149], v[54:57]
	s_waitcnt lgkmcnt(5)
	v_mfma_f32_16x16x32_bf16 v[46:49], v[122:125], v[154:157], v[46:49]
	v_mfma_f32_16x16x32_bf16 v[38:41], v[138:141], v[154:157], v[38:41]
	s_waitcnt lgkmcnt(3)
	v_mfma_f32_16x16x32_bf16 v[30:33], v[122:125], v[176:179], v[30:33]
	v_mfma_f32_16x16x32_bf16 v[22:25], v[138:141], v[176:179], v[22:25]
	s_waitcnt lgkmcnt(1)
	v_mfma_f32_16x16x32_bf16 v[14:17], v[122:125], v[206:209], v[14:17]
	v_mfma_f32_16x16x32_bf16 v[6:9], v[138:141], v[206:209], v[6:9]
	v_mfma_f32_16x16x32_bf16 v[62:65], v[126:129], v[150:153], v[62:65]
	v_mfma_f32_16x16x32_bf16 v[54:57], v[142:145], v[150:153], v[54:57]
	v_mfma_f32_16x16x32_bf16 v[46:49], v[126:129], v[158:161], v[46:49]
	v_mfma_f32_16x16x32_bf16 v[38:41], v[142:145], v[158:161], v[38:41]
	v_mfma_f32_16x16x32_bf16 v[30:33], v[126:129], v[202:205], v[30:33]
	v_mfma_f32_16x16x32_bf16 v[22:25], v[142:145], v[202:205], v[22:25]
	s_waitcnt lgkmcnt(0)
	v_mfma_f32_16x16x32_bf16 v[14:17], v[126:129], v[210:213], v[14:17]
	v_mfma_f32_16x16x32_bf16 v[6:9], v[142:145], v[210:213], v[6:9]
	s_barrier
	s_sub_u32 m0, s53, 0x80
	s_nop 0
	global_load_lds_dwordx4 v240, s[26:27] offset:128
	s_sub_u32 m0, s56, 0x80
	s_nop 0
	global_load_lds_dwordx4 v241, s[26:27] offset:128
	s_waitcnt vmcnt(6)
	s_barrier
	v_mfma_f32_16x16x32_bf16 v[58:61], v[214:217], v[146:149], v[58:61]
	v_mfma_f32_16x16x32_bf16 v[50:53], v[222:225], v[146:149], v[50:53]
	v_mfma_f32_16x16x32_bf16 v[42:45], v[214:217], v[154:157], v[42:45]
	v_mfma_f32_16x16x32_bf16 v[34:37], v[222:225], v[154:157], v[34:37]
	v_mfma_f32_16x16x32_bf16 v[26:29], v[214:217], v[176:179], v[26:29]
	v_mfma_f32_16x16x32_bf16 v[18:21], v[222:225], v[176:179], v[18:21]
	v_mfma_f32_16x16x32_bf16 v[10:13], v[214:217], v[206:209], v[10:13]
	v_mfma_f32_16x16x32_bf16 v[2:5], v[222:225], v[206:209], v[2:5]
	v_mfma_f32_16x16x32_bf16 v[58:61], v[218:221], v[150:153], v[58:61]
	v_mfma_f32_16x16x32_bf16 v[50:53], v[226:229], v[150:153], v[50:53]
	v_mfma_f32_16x16x32_bf16 v[42:45], v[218:221], v[158:161], v[42:45]
	v_mfma_f32_16x16x32_bf16 v[34:37], v[226:229], v[158:161], v[34:37]
	v_mfma_f32_16x16x32_bf16 v[26:29], v[218:221], v[202:205], v[26:29]
	v_mfma_f32_16x16x32_bf16 v[18:21], v[226:229], v[202:205], v[18:21]
	v_mfma_f32_16x16x32_bf16 v[10:13], v[218:221], v[210:213], v[10:13]
	v_mfma_f32_16x16x32_bf16 v[2:5], v[226:229], v[210:213], v[2:5]
	s_add_u32 s0, s0, 0x100
	s_addc_u32 s1, s1, 0
	s_add_u32 s28, s28, 0x100
	s_addc_u32 s29, s29, 0
	s_cmp_ge_i32 s36, s57
	s_mov_b32 s2, s36
	s_barrier
	s_cbranch_scc0 .LBB0_1104
	s_branch .LBB0_1095

.LBB0_1255:
	ds_read_b128 v[146:149], v177
	ds_read_b128 v[150:153], v178
	ds_read_b128 v[154:157], v179
	ds_read_b128 v[158:161], v180
	s_add_i32 s72, s2, 2
	s_add_u32 s28, s26, 0x80
	s_addc_u32 s3, s27, 0
	s_cmp_eq_u32 s64, s2
	s_cselect_b32 s2, s54, s28
	s_cselect_b32 s3, s55, s3
	s_cselect_b32 s29, s1, s53
	s_cselect_b32 s28, s0, s37
	s_mov_b32 m0, s66
	ds_read_b128 v[164:167], v174
	ds_read_b128 v[168:171], v174 offset:1024
	ds_read_b128 v[194:197], v174 offset:2048
	ds_read_b128 v[198:201], v174 offset:3072
	ds_read_b128 v[206:209], v174 offset:4096
	ds_read_b128 v[210:213], v174 offset:5120
	ds_read_b128 v[214:217], v174 offset:6144
	ds_read_b128 v[218:221], v174 offset:7168
	global_load_lds_dwordx4 v138, s[26:27]
	s_mov_b32 m0, s67
	s_nop 0
	global_load_lds_dwordx4 v140, s[26:27]
	s_waitcnt lgkmcnt(8)
	s_barrier
	s_waitcnt lgkmcnt(7)
	v_mfma_f32_16x16x32_bf16 v[130:133], v[146:149], v[164:167], v[130:133]
	v_mfma_f32_16x16x32_bf16 v[126:129], v[154:157], v[164:167], v[126:129]
	s_waitcnt lgkmcnt(5)
	v_mfma_f32_16x16x32_bf16 v[114:117], v[146:149], v[194:197], v[114:117]
	v_mfma_f32_16x16x32_bf16 v[110:113], v[154:157], v[194:197], v[110:113]
	s_waitcnt lgkmcnt(3)
	v_mfma_f32_16x16x32_bf16 v[98:101], v[146:149], v[206:209], v[98:101]
	v_mfma_f32_16x16x32_bf16 v[94:97], v[154:157], v[206:209], v[94:97]
	s_waitcnt lgkmcnt(1)
	v_mfma_f32_16x16x32_bf16 v[82:85], v[146:149], v[214:217], v[82:85]
	v_mfma_f32_16x16x32_bf16 v[78:81], v[154:157], v[214:217], v[78:81]
	v_mfma_f32_16x16x32_bf16 v[130:133], v[150:153], v[168:171], v[130:133]
	v_mfma_f32_16x16x32_bf16 v[126:129], v[158:161], v[168:171], v[126:129]
	v_mfma_f32_16x16x32_bf16 v[114:117], v[150:153], v[198:201], v[114:117]
	v_mfma_f32_16x16x32_bf16 v[110:113], v[158:161], v[198:201], v[110:113]
	v_mfma_f32_16x16x32_bf16 v[98:101], v[150:153], v[210:213], v[98:101]
	v_mfma_f32_16x16x32_bf16 v[94:97], v[158:161], v[210:213], v[94:97]
	s_waitcnt lgkmcnt(0)
	v_mfma_f32_16x16x32_bf16 v[82:85], v[150:153], v[218:221], v[82:85]
	v_mfma_f32_16x16x32_bf16 v[78:81], v[158:161], v[218:221], v[78:81]
	s_barrier
	s_mov_b32 m0, s38
	ds_read_b128 v[222:225], v181
	ds_read_b128 v[226:229], v182
	ds_read_b128 v[230:233], v183
	ds_read_b128 v[234:237], v184
	global_load_lds_dwordx4 v134, s[28:29]
	s_mov_b32 m0, s39
	s_nop 0
	global_load_lds_dwordx4 v136, s[28:29]
	s_barrier
	s_waitcnt lgkmcnt(3)
	v_mfma_f32_16x16x32_bf16 v[122:125], v[222:225], v[164:167], v[122:125]
	s_waitcnt lgkmcnt(1)
	v_mfma_f32_16x16x32_bf16 v[118:121], v[230:233], v[164:167], v[118:121]
	v_mfma_f32_16x16x32_bf16 v[106:109], v[222:225], v[194:197], v[106:109]
	v_mfma_f32_16x16x32_bf16 v[102:105], v[230:233], v[194:197], v[102:105]
	v_mfma_f32_16x16x32_bf16 v[90:93], v[222:225], v[206:209], v[90:93]
	v_mfma_f32_16x16x32_bf16 v[86:89], v[230:233], v[206:209], v[86:89]
	v_mfma_f32_16x16x32_bf16 v[74:77], v[222:225], v[214:217], v[74:77]
	v_mfma_f32_16x16x32_bf16 v[68:71], v[230:233], v[214:217], v[70:73]
	v_mfma_f32_16x16x32_bf16 v[122:125], v[226:229], v[168:171], v[122:125]
	s_waitcnt lgkmcnt(0)
	v_mfma_f32_16x16x32_bf16 v[118:121], v[234:237], v[168:171], v[118:121]
	v_mfma_f32_16x16x32_bf16 v[106:109], v[226:229], v[198:201], v[106:109]
	v_mfma_f32_16x16x32_bf16 v[102:105], v[234:237], v[198:201], v[102:105]
	v_mfma_f32_16x16x32_bf16 v[90:93], v[226:229], v[210:213], v[90:93]
	v_mfma_f32_16x16x32_bf16 v[86:89], v[234:237], v[210:213], v[86:89]
	v_mfma_f32_16x16x32_bf16 v[74:77], v[226:229], v[218:221], v[74:77]
	v_mfma_f32_16x16x32_bf16 v[68:71], v[234:237], v[218:221], v[68:71]
	s_mov_b32 m0, s35
	s_barrier
	ds_read_b128 v[164:167], v174 offset:16384
	ds_read_b128 v[168:171], v174 offset:17408
	ds_read_b128 v[194:197], v174 offset:18432
	ds_read_b128 v[198:201], v174 offset:19456
	ds_read_b128 v[206:209], v174 offset:20480
	ds_read_b128 v[210:213], v174 offset:21504
	ds_read_b128 v[214:217], v174 offset:22528
	ds_read_b128 v[218:221], v174 offset:23552
	global_load_lds_dwordx4 v134, s[2:3]
	s_mov_b32 m0, s40
	s_nop 0
	global_load_lds_dwordx4 v136, s[2:3]
	s_barrier
	s_waitcnt lgkmcnt(7)
	v_mfma_f32_16x16x32_bf16 v[62:65], v[146:149], v[164:167], v[62:65]
	v_mfma_f32_16x16x32_bf16 v[58:61], v[154:157], v[164:167], v[58:61]
	s_waitcnt lgkmcnt(5)
	v_mfma_f32_16x16x32_bf16 v[46:49], v[146:149], v[194:197], v[46:49]
	v_mfma_f32_16x16x32_bf16 v[42:45], v[154:157], v[194:197], v[42:45]
	s_waitcnt lgkmcnt(3)
	v_mfma_f32_16x16x32_bf16 v[30:33], v[146:149], v[206:209], v[30:33]
	v_mfma_f32_16x16x32_bf16 v[26:29], v[154:157], v[206:209], v[26:29]
	s_waitcnt lgkmcnt(1)
	v_mfma_f32_16x16x32_bf16 v[14:17], v[146:149], v[214:217], v[14:17]
	v_mfma_f32_16x16x32_bf16 v[10:13], v[154:157], v[214:217], v[10:13]
	v_mfma_f32_16x16x32_bf16 v[62:65], v[150:153], v[168:171], v[62:65]
	v_mfma_f32_16x16x32_bf16 v[58:61], v[158:161], v[168:171], v[58:61]
	v_mfma_f32_16x16x32_bf16 v[46:49], v[150:153], v[198:201], v[46:49]
	v_mfma_f32_16x16x32_bf16 v[42:45], v[158:161], v[198:201], v[42:45]
	v_mfma_f32_16x16x32_bf16 v[30:33], v[150:153], v[210:213], v[30:33]
	v_mfma_f32_16x16x32_bf16 v[26:29], v[158:161], v[210:213], v[26:29]
	s_waitcnt lgkmcnt(0)
	v_mfma_f32_16x16x32_bf16 v[14:17], v[150:153], v[218:221], v[14:17]
	v_mfma_f32_16x16x32_bf16 v[10:13], v[158:161], v[218:221], v[10:13]
	s_barrier
	s_mov_b32 m0, s41
	s_nop 0
	global_load_lds_dwordx4 v249, s[28:29]
	s_mov_b32 m0, s42
	s_nop 0
	global_load_lds_dwordx4 v248, s[28:29]
	s_waitcnt vmcnt(6)
	s_barrier
	v_mfma_f32_16x16x32_bf16 v[54:57], v[222:225], v[164:167], v[54:57]
	v_mfma_f32_16x16x32_bf16 v[50:53], v[230:233], v[164:167], v[50:53]
	v_mfma_f32_16x16x32_bf16 v[38:41], v[222:225], v[194:197], v[38:41]
	v_mfma_f32_16x16x32_bf16 v[34:37], v[230:233], v[194:197], v[34:37]
	v_mfma_f32_16x16x32_bf16 v[22:25], v[222:225], v[206:209], v[22:25]
	v_mfma_f32_16x16x32_bf16 v[18:21], v[230:233], v[206:209], v[18:21]
	v_mfma_f32_16x16x32_bf16 v[6:9], v[222:225], v[214:217], v[6:9]
	v_mfma_f32_16x16x32_bf16 v[2:5], v[230:233], v[214:217], v[2:5]
	v_mfma_f32_16x16x32_bf16 v[54:57], v[226:229], v[168:171], v[54:57]
	v_mfma_f32_16x16x32_bf16 v[50:53], v[234:237], v[168:171], v[50:53]
	v_mfma_f32_16x16x32_bf16 v[38:41], v[226:229], v[198:201], v[38:41]
	v_mfma_f32_16x16x32_bf16 v[34:37], v[234:237], v[198:201], v[34:37]
	v_mfma_f32_16x16x32_bf16 v[22:25], v[226:229], v[210:213], v[22:25]
	v_mfma_f32_16x16x32_bf16 v[18:21], v[234:237], v[210:213], v[18:21]
	v_mfma_f32_16x16x32_bf16 v[6:9], v[226:229], v[218:221], v[6:9]
	v_mfma_f32_16x16x32_bf16 v[2:5], v[234:237], v[218:221], v[2:5]
	s_barrier
	ds_read_b128 v[146:149], v185
	ds_read_b128 v[150:153], v186
	ds_read_b128 v[154:157], v187
	ds_read_b128 v[158:161], v188
	s_mov_b32 m0, s43
	ds_read_b128 v[164:167], v174 offset:32768
	ds_read_b128 v[168:171], v174 offset:33792
	ds_read_b128 v[194:197], v174 offset:34816
	ds_read_b128 v[198:201], v174 offset:35840
	ds_read_b128 v[206:209], v174 offset:36864
	ds_read_b128 v[210:213], v174 offset:37888
	ds_read_b128 v[214:217], v174 offset:38912
	ds_read_b128 v[218:221], v174 offset:39936
	global_load_lds_dwordx4 v249, s[2:3]
	s_mov_b32 m0, s45
	s_nop 0
	global_load_lds_dwordx4 v248, s[2:3]
	s_waitcnt lgkmcnt(8)
	s_barrier
	s_waitcnt lgkmcnt(7)
	v_mfma_f32_16x16x32_bf16 v[130:133], v[146:149], v[164:167], v[130:133]
	v_mfma_f32_16x16x32_bf16 v[126:129], v[154:157], v[164:167], v[126:129]
	s_waitcnt lgkmcnt(5)
	v_mfma_f32_16x16x32_bf16 v[114:117], v[146:149], v[194:197], v[114:117]
	v_mfma_f32_16x16x32_bf16 v[110:113], v[154:157], v[194:197], v[110:113]
	s_waitcnt lgkmcnt(3)
	v_mfma_f32_16x16x32_bf16 v[98:101], v[146:149], v[206:209], v[98:101]
	v_mfma_f32_16x16x32_bf16 v[94:97], v[154:157], v[206:209], v[94:97]
	s_waitcnt lgkmcnt(1)
	v_mfma_f32_16x16x32_bf16 v[82:85], v[146:149], v[214:217], v[82:85]
	v_mfma_f32_16x16x32_bf16 v[78:81], v[154:157], v[214:217], v[78:81]
	v_mfma_f32_16x16x32_bf16 v[130:133], v[150:153], v[168:171], v[130:133]
	v_mfma_f32_16x16x32_bf16 v[126:129], v[158:161], v[168:171], v[126:129]
	v_mfma_f32_16x16x32_bf16 v[114:117], v[150:153], v[198:201], v[114:117]
	v_mfma_f32_16x16x32_bf16 v[110:113], v[158:161], v[198:201], v[110:113]
	v_mfma_f32_16x16x32_bf16 v[98:101], v[150:153], v[210:213], v[98:101]
	v_mfma_f32_16x16x32_bf16 v[94:97], v[158:161], v[210:213], v[94:97]
	s_waitcnt lgkmcnt(0)
	v_mfma_f32_16x16x32_bf16 v[82:85], v[150:153], v[218:221], v[82:85]
	v_mfma_f32_16x16x32_bf16 v[78:81], v[158:161], v[218:221], v[78:81]
	s_barrier
	s_sub_u32 m0, s50, 0x80
	ds_read_b128 v[222:225], v189
	ds_read_b128 v[226:229], v190
	ds_read_b128 v[230:233], v191
	ds_read_b128 v[234:237], v192
	global_load_lds_dwordx4 v134, s[28:29] offset:128
	s_sub_u32 m0, s51, 0x80
	s_nop 0
	global_load_lds_dwordx4 v136, s[28:29] offset:128
	s_barrier
	s_waitcnt lgkmcnt(3)
	v_mfma_f32_16x16x32_bf16 v[122:125], v[222:225], v[164:167], v[122:125]
	s_waitcnt lgkmcnt(1)
	v_mfma_f32_16x16x32_bf16 v[118:121], v[230:233], v[164:167], v[118:121]
	v_mfma_f32_16x16x32_bf16 v[106:109], v[222:225], v[194:197], v[106:109]
	v_mfma_f32_16x16x32_bf16 v[102:105], v[230:233], v[194:197], v[102:105]
	v_mfma_f32_16x16x32_bf16 v[90:93], v[222:225], v[206:209], v[90:93]
	v_mfma_f32_16x16x32_bf16 v[86:89], v[230:233], v[206:209], v[86:89]
	v_mfma_f32_16x16x32_bf16 v[72:75], v[222:225], v[214:217], v[74:77]
	v_mfma_f32_16x16x32_bf16 v[68:71], v[230:233], v[214:217], v[68:71]
	v_mfma_f32_16x16x32_bf16 v[122:125], v[226:229], v[168:171], v[122:125]
	s_waitcnt lgkmcnt(0)
	v_mfma_f32_16x16x32_bf16 v[118:121], v[234:237], v[168:171], v[118:121]
	v_mfma_f32_16x16x32_bf16 v[106:109], v[226:229], v[198:201], v[106:109]
	v_mfma_f32_16x16x32_bf16 v[102:105], v[234:237], v[198:201], v[102:105]
	v_mfma_f32_16x16x32_bf16 v[90:93], v[226:229], v[210:213], v[90:93]
	v_mfma_f32_16x16x32_bf16 v[86:89], v[234:237], v[210:213], v[86:89]
	v_mfma_f32_16x16x32_bf16 v[74:77], v[226:229], v[218:221], v[72:75]
	v_mfma_f32_16x16x32_bf16 v[70:73], v[234:237], v[218:221], v[68:71]
	s_sub_u32 m0, s60, 0x80
	s_nop 0
	s_barrier
	ds_read_b128 v[164:167], v174 offset:49152
	ds_read_b128 v[168:171], v174 offset:50176
	ds_read_b128 v[194:197], v174 offset:51200
	ds_read_b128 v[198:201], v174 offset:52224
	ds_read_b128 v[206:209], v174 offset:53248
	ds_read_b128 v[210:213], v174 offset:54272
	ds_read_b128 v[214:217], v174 offset:55296
	ds_read_b128 v[218:221], v174 offset:56320
	global_load_lds_dwordx4 v134, s[2:3] offset:128
	s_sub_u32 m0, s61, 0x80
	s_nop 0
	global_load_lds_dwordx4 v136, s[2:3] offset:128
	s_barrier
	s_waitcnt lgkmcnt(7)
	v_mfma_f32_16x16x32_bf16 v[62:65], v[146:149], v[164:167], v[62:65]
	v_mfma_f32_16x16x32_bf16 v[58:61], v[154:157], v[164:167], v[58:61]
	s_waitcnt lgkmcnt(5)
	v_mfma_f32_16x16x32_bf16 v[46:49], v[146:149], v[194:197], v[46:49]
	v_mfma_f32_16x16x32_bf16 v[42:45], v[154:157], v[194:197], v[42:45]
	s_waitcnt lgkmcnt(3)
	v_mfma_f32_16x16x32_bf16 v[30:33], v[146:149], v[206:209], v[30:33]
	v_mfma_f32_16x16x32_bf16 v[26:29], v[154:157], v[206:209], v[26:29]
	s_waitcnt lgkmcnt(1)
	v_mfma_f32_16x16x32_bf16 v[14:17], v[146:149], v[214:217], v[14:17]
	v_mfma_f32_16x16x32_bf16 v[10:13], v[154:157], v[214:217], v[10:13]
	v_mfma_f32_16x16x32_bf16 v[62:65], v[150:153], v[168:171], v[62:65]
	v_mfma_f32_16x16x32_bf16 v[58:61], v[158:161], v[168:171], v[58:61]
	v_mfma_f32_16x16x32_bf16 v[46:49], v[150:153], v[198:201], v[46:49]
	v_mfma_f32_16x16x32_bf16 v[42:45], v[158:161], v[198:201], v[42:45]
	v_mfma_f32_16x16x32_bf16 v[30:33], v[150:153], v[210:213], v[30:33]
	v_mfma_f32_16x16x32_bf16 v[26:29], v[158:161], v[210:213], v[26:29]
	s_waitcnt lgkmcnt(0)
	v_mfma_f32_16x16x32_bf16 v[14:17], v[150:153], v[218:221], v[14:17]
	v_mfma_f32_16x16x32_bf16 v[10:13], v[158:161], v[218:221], v[10:13]
	s_barrier
	s_sub_u32 m0, s62, 0x80
	s_nop 0
	global_load_lds_dwordx4 v249, s[28:29] offset:128
	s_sub_u32 m0, s63, 0x80
	s_nop 0
	global_load_lds_dwordx4 v248, s[28:29] offset:128
	s_waitcnt vmcnt(6)
	s_barrier
	v_mfma_f32_16x16x32_bf16 v[54:57], v[222:225], v[164:167], v[54:57]
	v_mfma_f32_16x16x32_bf16 v[50:53], v[230:233], v[164:167], v[50:53]
	v_mfma_f32_16x16x32_bf16 v[38:41], v[222:225], v[194:197], v[38:41]
	v_mfma_f32_16x16x32_bf16 v[34:37], v[230:233], v[194:197], v[34:37]
	v_mfma_f32_16x16x32_bf16 v[22:25], v[222:225], v[206:209], v[22:25]
	v_mfma_f32_16x16x32_bf16 v[18:21], v[230:233], v[206:209], v[18:21]
	v_mfma_f32_16x16x32_bf16 v[6:9], v[222:225], v[214:217], v[6:9]
	v_mfma_f32_16x16x32_bf16 v[2:5], v[230:233], v[214:217], v[2:5]
	v_mfma_f32_16x16x32_bf16 v[54:57], v[226:229], v[168:171], v[54:57]
	v_mfma_f32_16x16x32_bf16 v[50:53], v[234:237], v[168:171], v[50:53]
	v_mfma_f32_16x16x32_bf16 v[38:41], v[226:229], v[198:201], v[38:41]
	v_mfma_f32_16x16x32_bf16 v[34:37], v[234:237], v[198:201], v[34:37]
	v_mfma_f32_16x16x32_bf16 v[22:25], v[226:229], v[210:213], v[22:25]
	v_mfma_f32_16x16x32_bf16 v[18:21], v[234:237], v[210:213], v[18:21]
	v_mfma_f32_16x16x32_bf16 v[6:9], v[226:229], v[218:221], v[6:9]
	v_mfma_f32_16x16x32_bf16 v[2:5], v[234:237], v[218:221], v[2:5]
	s_add_u32 s26, s26, 0x100
	s_addc_u32 s27, s27, 0
	s_add_u32 s37, s37, 0x100
	s_addc_u32 s53, s53, 0
	s_cmp_ge_i32 s72, s49
	s_mov_b32 s2, s72
	s_barrier
	s_cbranch_scc0 .LBB0_1255
